# P0 memory-RMSNorm loop: hoist the seven serialised gain-chunk loads, drop the per-chunk vmcnt(0) ladder
# speedup vs baseline: 1.0014x; 1.0014x over previous
; #define GAS __attribute__((address_space(1)))
; __device__ __forceinline__ void rms_row_to_bf16(const float* xrow, const float* g, bf16* orow, int lane) {
;     const GAS f32x4* xr = (const GAS f32x4*)xrow + lane; const GAS f32x4* gr = (const GAS f32x4*)g + lane;
;     f32x4 v[8]; float s = 0.f;
; #pragma unroll
;     for (int j = 0; j < 8; ++j) { v[j] = xr[64 * j]; s += (v[j].x * v[j].x + v[j].y * v[j].y) + (v[j].z * v[j].z + v[j].w * v[j].w); }
;     const float rstd = 1.0f / sqrtf(wave_sum(s) * (1.f / DM) + RMS_EPS);
; __global__ void __launch_bounds__(NWAVES * 64, 2) fwd(Args args) {
;     ...
;         for (int t = gw; t < 4 * MEMROWS; t += NGW) { const int i = t / MEMROWS, r = t - i * MEMROWS;
;             const float* mr = r < NMEM ? mem_prompt + (size_t)r * DM : mem_sample + (size_t)(r - NMEM) * DM;
;             rms_row_to_bf16(mr, g_mem + i * DM, MEMN + (size_t)t * DM, lane); }
.LBB0_123:
	s_mul_hi_i32 s4, s21, 0x66666667
	s_lshr_b32 s5, s4, 31
	s_ashr_i32 s4, s4, 9
	s_add_i32 s24, s4, s5
	s_mul_i32 s4, s24, 0xfffffb00
	s_add_i32 s4, s21, s4
	s_add_i32 s22, s4, 0xffffff00
	s_ashr_i32 s5, s4, 31
	s_cmpk_lt_i32 s4, 0x100
	s_cselect_b32 s5, s5, 0
	s_cselect_b32 s4, s4, s22
	s_cselect_b32 s23, s9, s11
	s_cselect_b32 s22, s8, s10
	s_lshl_b64 s[4:5], s[4:5], 13
	s_add_u32 s22, s22, s4
	s_addc_u32 s23, s23, s5
	v_lshl_add_u64 v[2:3], s[22:23], 0, v[34:35]
	s_lshl_b32 s4, s24, 11
	global_load_dwordx4 v[26:29], v34, s[22:23]
	global_load_dwordx4 v[22:25], v34, s[22:23] offset:1024
	global_load_dwordx4 v[18:21], v34, s[22:23] offset:2048
	global_load_dwordx4 v[6:9], v34, s[22:23] offset:3072
	v_add_co_u32_e32 v58, vcc, s13, v2
	s_ashr_i32 s5, s4, 31
	s_nop 0
	v_addc_co_u32_e32 v59, vcc, 0, v3, vcc
	v_lshl_add_u64 v[42:43], s[4:5], 2, v[38:39]
	global_load_dwordx4 v[14:17], v[58:59], off offset:1024
	global_load_dwordx4 v[30:33], v[58:59], off
	global_load_dwordx4 v[2:5], v[58:59], off offset:3072
	global_load_dwordx4 v[10:13], v[58:59], off offset:2048
	global_load_dwordx4 v[54:57], v[42:43], off
	v_add_co_u32_e32 v228, vcc, s13, v42
	s_nop 1
	v_addc_co_u32_e32 v229, vcc, 0, v43, vcc
	global_load_dwordx4 v[200:203], v[42:43], off offset:1024
	global_load_dwordx4 v[204:207], v[42:43], off offset:2048
	global_load_dwordx4 v[208:211], v[42:43], off offset:3072
	global_load_dwordx4 v[212:215], v[228:229], off
	global_load_dwordx4 v[216:219], v[228:229], off offset:1024
	global_load_dwordx4 v[220:223], v[228:229], off offset:2048
	global_load_dwordx4 v[224:227], v[228:229], off offset:3072
	s_add_i32 s21, s21, s14
	s_cmpk_gt_i32 s21, 0x13ff
	s_waitcnt vmcnt(15)
	v_mov_b32_e32 v60, v27
	s_waitcnt vmcnt(14)
	v_mov_b32_e32 v61, v23
	s_waitcnt vmcnt(13)
	v_pk_mul_f32 v[64:65], v[20:21], v[20:21]
	v_pk_mul_f32 v[66:67], v[18:19], v[18:19]
	v_mov_b32_e32 v68, v29
	v_mov_b32_e32 v69, v25
	v_mov_b32_e32 v58, v26
	v_mov_b32_e32 v59, v22
	v_mov_b32_e32 v62, v28
	v_mov_b32_e32 v63, v24
	v_mov_b32_e32 v74, v26
	v_mov_b32_e32 v75, v28
	v_mov_b32_e32 v28, v27
	v_mov_b32_e32 v26, v22
	v_mov_b32_e32 v27, v24
	v_mov_b32_e32 v24, v23
	v_pk_mov_b32 v[22:23], v[66:67], v[64:65] op_sel:[1,0]
	v_mov_b32_e32 v67, v65
	v_pk_mul_f32 v[60:61], v[60:61], v[60:61]
	v_pk_mul_f32 v[64:65], v[68:69], v[68:69]
	v_pk_fma_f32 v[58:59], v[58:59], v[58:59], v[60:61]
	v_pk_fma_f32 v[60:61], v[62:63], v[62:63], v[64:65]
	s_waitcnt vmcnt(12)
	v_mul_f32_e32 v70, v7, v7
	v_mul_f32_e32 v72, v9, v9
	v_pk_add_f32 v[22:23], v[22:23], v[66:67]
	s_waitcnt vmcnt(0)
	v_mov_b32_e32 v76, v54
	v_mov_b32_e32 v77, v56
	v_mov_b32_e32 v56, v55
	v_pk_add_f32 v[54:55], v[58:59], v[60:61]
	v_pk_fma_f32 v[68:69], v[6:7], v[6:7], v[70:71] op_sel_hi:[1,1,0]
	v_pk_fma_f32 v[70:71], v[8:9], v[8:9], v[72:73] op_sel_hi:[1,1,0]
	v_mul_f32_e32 v79, v31, v31
	v_mul_f32_e32 v80, v30, v30
	v_pk_add_f32 v[22:23], v[22:23], v[22:23] op_sel:[0,1] op_sel_hi:[1,0]
	v_pk_add_f32 v[54:55], v[54:55], v[54:55] op_sel:[0,1] op_sel_hi:[1,0]
	v_pk_mul_f32 v[62:63], v[16:17], v[16:17]
	v_pk_mul_f32 v[64:65], v[14:15], v[14:15]
	v_mul_f32_e32 v69, v32, v32
	v_mul_f32_e32 v71, v33, v33
	v_mul_f32_e32 v66, v11, v11
	v_mov_b32_e32 v23, v79
	v_mov_b32_e32 v55, v80
	v_pk_mov_b32 v[58:59], v[64:65], v[62:63] op_sel:[1,0]
	v_mov_b32_e32 v65, v63
	v_pk_fma_f32 v[60:61], v[10:11], v[10:11], v[66:67] op_sel_hi:[1,1,0]
	v_pk_add_f32 v[66:67], v[68:69], v[70:71]
	v_pk_add_f32 v[22:23], v[54:55], v[22:23]
	v_mul_f32_e32 v73, v4, v4
	v_mul_f32_e32 v72, v13, v13
	v_pk_add_f32 v[58:59], v[58:59], v[64:65]
	v_pk_add_f32 v[22:23], v[22:23], v[66:67]
	v_mul_f32_e32 v78, v5, v5
	v_mul_f32_e32 v81, v3, v3
	v_mul_f32_e32 v82, v2, v2
	v_pk_fma_f32 v[62:63], v[12:13], v[12:13], v[72:73] op_sel_hi:[1,1,0]
	v_pk_add_f32 v[58:59], v[58:59], v[58:59] op_sel:[0,1] op_sel_hi:[1,0]
	v_pk_add_f32 v[22:23], v[22:23], v[22:23] op_sel:[0,1] op_sel_hi:[1,0]
	v_mov_b32_e32 v61, v73
	v_mov_b32_e32 v63, v78
	v_mov_b32_e32 v59, v81
	v_mov_b32_e32 v23, v82
	v_pk_add_f32 v[60:61], v[60:61], v[62:63]
	v_pk_add_f32 v[22:23], v[22:23], v[58:59]
	s_nop 0
	v_pk_add_f32 v[22:23], v[22:23], v[60:61]
	s_nop 0
	v_add_f32_e32 v22, v22, v23
	ds_bpermute_b32 v23, v45, v22
	s_waitcnt lgkmcnt(0)
	v_add_f32_e32 v22, v22, v23
	ds_bpermute_b32 v23, v46, v22
	s_waitcnt lgkmcnt(0)
	v_add_f32_e32 v22, v22, v23
	ds_bpermute_b32 v23, v48, v22
	s_waitcnt lgkmcnt(0)
	v_add_f32_e32 v22, v22, v23
	ds_bpermute_b32 v23, v49, v22
	s_waitcnt lgkmcnt(0)
	v_add_f32_e32 v22, v22, v23
	ds_bpermute_b32 v23, v50, v22
	s_waitcnt lgkmcnt(0)
	v_add_f32_e32 v22, v22, v23
	ds_bpermute_b32 v23, v51, v22
	s_waitcnt lgkmcnt(0)
; #define GAS __attribute__((address_space(1)))
; __device__ __forceinline__ unsigned pk2(float lo, float hi) { return f2bf(lo) | (f2bf(hi) << 16); }
; __device__ __forceinline__ void rms_row_to_bf16(const float* xrow, const float* g, bf16* orow, int lane) {
;     ...
;     const float rstd = 1.0f / sqrtf(wave_sum(s) * (1.f / DM) + RMS_EPS);
;     GAS v2u* o8 = (GAS v2u*)orow + lane;
; #pragma unroll
;     for (int j = 0; j < 8; ++j) { const f32x4 gv = gr[64 * j]; v2u o; o.x = pk2(v[j].x * rstd * gv.x, v[j].y * rstd * gv.y); o.y = pk2(v[j].z * rstd * gv.z, v[j].w * rstd * gv.w); o8[64 * j] = o; }
	v_add_f32_e32 v22, v22, v23
	v_fmamk_f32 v22, v22, 0x3a000000, v37
	v_mul_f32_e32 v23, 0x4f800000, v22
	v_cmp_gt_f32_e32 vcc, s15, v22
	s_nop 1
	v_cndmask_b32_e32 v22, v22, v23, vcc
	v_sqrt_f32_e32 v23, v22
	s_nop 0
	v_add_u32_e32 v54, -1, v23
	v_add_u32_e32 v55, 1, v23
	v_fma_f32 v58, -v54, v23, v22
	v_fma_f32 v59, -v55, v23, v22
	v_cmp_ge_f32_e64 s[4:5], 0, v58
	s_nop 1
	v_cndmask_b32_e64 v23, v23, v54, s[4:5]
	v_cmp_lt_f32_e64 s[4:5], 0, v59
	s_nop 1
	v_cndmask_b32_e64 v23, v23, v55, s[4:5]
	v_mul_f32_e32 v54, 0x37800000, v23
	v_cndmask_b32_e32 v23, v23, v54, vcc
	v_cmp_class_f32_e32 vcc, v22, v52
	s_nop 1
	v_cndmask_b32_e32 v22, v23, v22, vcc
	v_div_scale_f32 v23, s[4:5], v22, v22, 1.0
	v_rcp_f32_e32 v55, v23
	v_div_scale_f32 v54, vcc, 1.0, v22, 1.0
	v_fma_f32 v58, -v23, v55, 1.0
	v_fmac_f32_e32 v55, v58, v55
	v_mul_f32_e32 v58, v54, v55
	v_fma_f32 v59, -v23, v58, v54
	v_fmac_f32_e32 v58, v59, v55
	v_fma_f32 v23, -v23, v58, v54
	v_div_fmas_f32 v23, v23, v55, v58
	v_div_fixup_f32 v22, v23, v22, 1.0
	v_pk_mul_f32 v[28:29], v[28:29], v[22:23] op_sel_hi:[1,0]
	v_pk_mul_f32 v[54:55], v[74:75], v[22:23] op_sel_hi:[1,0]
	v_pk_mul_f32 v[58:59], v[26:27], v[22:23] op_sel_hi:[1,0]
	v_pk_mul_f32 v[26:27], v[76:77], v[54:55]
	v_pk_mul_f32 v[28:29], v[56:57], v[28:29]
	v_and_b32_sdwa v23, v27, v53 dst_sel:DWORD dst_unused:UNUSED_PAD src0_sel:WORD_1 src1_sel:DWORD
	v_and_b32_sdwa v55, v29, v53 dst_sel:DWORD dst_unused:UNUSED_PAD src0_sel:WORD_1 src1_sel:DWORD
	v_and_b32_sdwa v56, v28, v53 dst_sel:DWORD dst_unused:UNUSED_PAD src0_sel:WORD_1 src1_sel:DWORD
	v_and_b32_sdwa v54, v26, v53 dst_sel:DWORD dst_unused:UNUSED_PAD src0_sel:WORD_1 src1_sel:DWORD
	v_add3_u32 v23, v27, v23, s20
	v_add3_u32 v27, v29, v55, s20
	v_add3_u32 v28, v28, v56, s20
	v_add3_u32 v26, v26, v54, s20
	v_and_b32_e32 v27, 0xffff0000, v27
	v_and_b32_e32 v28, 0xffff0000, v28
	v_or_b32_sdwa v27, v27, v23 dst_sel:DWORD dst_unused:UNUSED_PAD src0_sel:DWORD src1_sel:WORD_1
	v_or_b32_sdwa v26, v28, v26 dst_sel:DWORD dst_unused:UNUSED_PAD src0_sel:DWORD src1_sel:WORD_1
	global_store_dwordx2 v[40:41], v[26:27], off
	s_nop 1
	v_mov_b64_e32 v[26:27], v[200:201]
	v_mov_b64_e32 v[28:29], v[202:203]
	v_pk_mul_f32 v[24:25], v[24:25], v[22:23] op_sel_hi:[1,0]
	v_mov_b32_e32 v55, v28
	v_mov_b32_e32 v28, v27
	v_mov_b32_e32 v54, v26
	v_pk_mul_f32 v[24:25], v[28:29], v[24:25]
	v_pk_mul_f32 v[26:27], v[54:55], v[58:59]
	v_and_b32_sdwa v29, v25, v53 dst_sel:DWORD dst_unused:UNUSED_PAD src0_sel:WORD_1 src1_sel:DWORD
	v_and_b32_sdwa v54, v24, v53 dst_sel:DWORD dst_unused:UNUSED_PAD src0_sel:WORD_1 src1_sel:DWORD
	v_and_b32_sdwa v23, v27, v53 dst_sel:DWORD dst_unused:UNUSED_PAD src0_sel:WORD_1 src1_sel:DWORD
	v_and_b32_sdwa v28, v26, v53 dst_sel:DWORD dst_unused:UNUSED_PAD src0_sel:WORD_1 src1_sel:DWORD
	v_add3_u32 v25, v25, v29, s20
	v_add3_u32 v24, v24, v54, s20
	v_add3_u32 v26, v26, v28, s20
	v_add3_u32 v23, v27, v23, s20
	v_and_b32_e32 v25, 0xffff0000, v25
	v_and_b32_e32 v24, 0xffff0000, v24
	v_or_b32_sdwa v25, v25, v23 dst_sel:DWORD dst_unused:UNUSED_PAD src0_sel:DWORD src1_sel:WORD_1
	v_or_b32_sdwa v24, v24, v26 dst_sel:DWORD dst_unused:UNUSED_PAD src0_sel:DWORD src1_sel:WORD_1
	global_store_dwordx2 v[40:41], v[24:25], off offset:512
	s_nop 1
	v_mov_b64_e32 v[24:25], v[204:205]
	v_mov_b64_e32 v[26:27], v[206:207]
	v_mov_b32_e32 v28, v18
	v_mov_b32_e32 v29, v20
	v_mov_b32_e32 v20, v19
	v_pk_mul_f32 v[18:19], v[28:29], v[22:23] op_sel_hi:[1,0]
	v_pk_mul_f32 v[20:21], v[20:21], v[22:23] op_sel_hi:[1,0]
	v_mov_b32_e32 v29, v26
	v_mov_b32_e32 v26, v25
	v_mov_b32_e32 v28, v24
	v_pk_mul_f32 v[20:21], v[26:27], v[20:21]
	v_pk_mul_f32 v[18:19], v[28:29], v[18:19]
	v_and_b32_sdwa v25, v21, v53 dst_sel:DWORD dst_unused:UNUSED_PAD src0_sel:WORD_1 src1_sel:DWORD
	v_and_b32_sdwa v26, v20, v53 dst_sel:DWORD dst_unused:UNUSED_PAD src0_sel:WORD_1 src1_sel:DWORD
	v_and_b32_sdwa v23, v19, v53 dst_sel:DWORD dst_unused:UNUSED_PAD src0_sel:WORD_1 src1_sel:DWORD
	v_and_b32_sdwa v24, v18, v53 dst_sel:DWORD dst_unused:UNUSED_PAD src0_sel:WORD_1 src1_sel:DWORD
	v_add3_u32 v21, v21, v25, s20
	v_add3_u32 v20, v20, v26, s20
	v_add3_u32 v18, v18, v24, s20
	v_add3_u32 v19, v19, v23, s20
	v_and_b32_e32 v21, 0xffff0000, v21
	v_and_b32_e32 v20, 0xffff0000, v20
	v_or_b32_sdwa v19, v21, v19 dst_sel:DWORD dst_unused:UNUSED_PAD src0_sel:DWORD src1_sel:WORD_1
	v_or_b32_sdwa v18, v20, v18 dst_sel:DWORD dst_unused:UNUSED_PAD src0_sel:DWORD src1_sel:WORD_1
	global_store_dwordx2 v[40:41], v[18:19], off offset:1024
	s_nop 1
	v_mov_b64_e32 v[18:19], v[208:209]
	v_mov_b64_e32 v[20:21], v[210:211]
	v_mov_b32_e32 v26, v6
	v_mov_b32_e32 v27, v8
	v_mov_b32_e32 v8, v7
	v_pk_mul_f32 v[6:7], v[26:27], v[22:23] op_sel_hi:[1,0]
	v_pk_mul_f32 v[8:9], v[8:9], v[22:23] op_sel_hi:[1,0]
	v_add_co_u32_e32 v24, vcc, s13, v42
	v_mov_b32_e32 v27, v20
	v_mov_b32_e32 v20, v19
	v_mov_b32_e32 v26, v18
	v_pk_mul_f32 v[8:9], v[8:9], v[20:21]
	v_pk_mul_f32 v[6:7], v[6:7], v[26:27]
	v_and_b32_sdwa v20, v9, v53 dst_sel:DWORD dst_unused:UNUSED_PAD src0_sel:WORD_1 src1_sel:DWORD
	v_and_b32_sdwa v21, v8, v53 dst_sel:DWORD dst_unused:UNUSED_PAD src0_sel:WORD_1 src1_sel:DWORD
	v_and_b32_sdwa v18, v7, v53 dst_sel:DWORD dst_unused:UNUSED_PAD src0_sel:WORD_1 src1_sel:DWORD
	v_and_b32_sdwa v19, v6, v53 dst_sel:DWORD dst_unused:UNUSED_PAD src0_sel:WORD_1 src1_sel:DWORD
	v_add3_u32 v9, v9, v20, s20
	v_add3_u32 v8, v8, v21, s20
; #define GAS __attribute__((address_space(1)))
; __device__ __forceinline__ unsigned pk2(float lo, float hi) { return f2bf(lo) | (f2bf(hi) << 16); }
; __device__ __forceinline__ void rms_row_to_bf16(const float* xrow, const float* g, bf16* orow, int lane) {
;     ...
;     GAS v2u* o8 = (GAS v2u*)orow + lane;
; #pragma unroll
;     for (int j = 0; j < 8; ++j) { const f32x4 gv = gr[64 * j]; v2u o; o.x = pk2(v[j].x * rstd * gv.x, v[j].y * rstd * gv.y); o.y = pk2(v[j].z * rstd * gv.z, v[j].w * rstd * gv.w); o8[64 * j] = o; }
	v_add3_u32 v6, v6, v19, s20
	v_add3_u32 v7, v7, v18, s20
	v_and_b32_e32 v9, 0xffff0000, v9
	v_and_b32_e32 v8, 0xffff0000, v8
	v_or_b32_sdwa v7, v9, v7 dst_sel:DWORD dst_unused:UNUSED_PAD src0_sel:DWORD src1_sel:WORD_1
	v_or_b32_sdwa v6, v8, v6 dst_sel:DWORD dst_unused:UNUSED_PAD src0_sel:DWORD src1_sel:WORD_1
	v_addc_co_u32_e32 v25, vcc, 0, v43, vcc
	global_store_dwordx2 v[40:41], v[6:7], off offset:1536
	s_nop 1
	v_mov_b64_e32 v[6:7], v[212:213]
	v_mov_b64_e32 v[8:9], v[214:215]
	v_mov_b32_e32 v19, v32
	v_mov_b32_e32 v32, v31
	v_mov_b32_e32 v18, v30
	v_pk_mul_f32 v[20:21], v[32:33], v[22:23] op_sel_hi:[1,0]
	v_pk_mul_f32 v[18:19], v[18:19], v[22:23] op_sel_hi:[1,0]
	v_mov_b32_e32 v27, v8
	v_mov_b32_e32 v8, v7
	v_mov_b32_e32 v26, v6
	v_pk_mul_f32 v[8:9], v[20:21], v[8:9]
	v_pk_mul_f32 v[6:7], v[18:19], v[26:27]
	v_and_b32_sdwa v20, v9, v53 dst_sel:DWORD dst_unused:UNUSED_PAD src0_sel:WORD_1 src1_sel:DWORD
	v_and_b32_sdwa v21, v8, v53 dst_sel:DWORD dst_unused:UNUSED_PAD src0_sel:WORD_1 src1_sel:DWORD
	v_and_b32_sdwa v18, v7, v53 dst_sel:DWORD dst_unused:UNUSED_PAD src0_sel:WORD_1 src1_sel:DWORD
	v_and_b32_sdwa v19, v6, v53 dst_sel:DWORD dst_unused:UNUSED_PAD src0_sel:WORD_1 src1_sel:DWORD
	v_add3_u32 v9, v9, v20, s20
	v_add3_u32 v8, v8, v21, s20
	v_add3_u32 v6, v6, v19, s20
	v_add3_u32 v7, v7, v18, s20
	v_and_b32_e32 v9, 0xffff0000, v9
	v_and_b32_e32 v8, 0xffff0000, v8
	v_or_b32_sdwa v7, v9, v7 dst_sel:DWORD dst_unused:UNUSED_PAD src0_sel:DWORD src1_sel:WORD_1
	v_or_b32_sdwa v6, v8, v6 dst_sel:DWORD dst_unused:UNUSED_PAD src0_sel:DWORD src1_sel:WORD_1
	global_store_dwordx2 v[40:41], v[6:7], off offset:2048
	s_nop 1
	v_mov_b64_e32 v[6:7], v[216:217]
	v_mov_b64_e32 v[8:9], v[218:219]
	v_mov_b32_e32 v18, v14
	v_mov_b32_e32 v19, v16
	v_mov_b32_e32 v16, v15
	v_pk_mul_f32 v[14:15], v[18:19], v[22:23] op_sel_hi:[1,0]
	v_pk_mul_f32 v[16:17], v[16:17], v[22:23] op_sel_hi:[1,0]
	v_mov_b32_e32 v19, v8
	v_mov_b32_e32 v8, v7
	v_mov_b32_e32 v18, v6
	v_pk_mul_f32 v[8:9], v[16:17], v[8:9]
	v_pk_mul_f32 v[6:7], v[14:15], v[18:19]
	v_and_b32_sdwa v16, v9, v53 dst_sel:DWORD dst_unused:UNUSED_PAD src0_sel:WORD_1 src1_sel:DWORD
	v_and_b32_sdwa v17, v8, v53 dst_sel:DWORD dst_unused:UNUSED_PAD src0_sel:WORD_1 src1_sel:DWORD
	v_and_b32_sdwa v14, v7, v53 dst_sel:DWORD dst_unused:UNUSED_PAD src0_sel:WORD_1 src1_sel:DWORD
	v_and_b32_sdwa v15, v6, v53 dst_sel:DWORD dst_unused:UNUSED_PAD src0_sel:WORD_1 src1_sel:DWORD
	v_add3_u32 v9, v9, v16, s20
	v_add3_u32 v8, v8, v17, s20
	v_add3_u32 v6, v6, v15, s20
	v_add3_u32 v7, v7, v14, s20
	v_and_b32_e32 v9, 0xffff0000, v9
	v_and_b32_e32 v8, 0xffff0000, v8
	v_or_b32_sdwa v7, v9, v7 dst_sel:DWORD dst_unused:UNUSED_PAD src0_sel:DWORD src1_sel:WORD_1
	v_or_b32_sdwa v6, v8, v6 dst_sel:DWORD dst_unused:UNUSED_PAD src0_sel:DWORD src1_sel:WORD_1
	global_store_dwordx2 v[40:41], v[6:7], off offset:2560
	s_nop 1
	v_mov_b64_e32 v[6:7], v[220:221]
	v_mov_b64_e32 v[8:9], v[222:223]
	v_mov_b32_e32 v14, v10
	v_mov_b32_e32 v15, v12
	v_mov_b32_e32 v12, v11
	v_pk_mul_f32 v[10:11], v[14:15], v[22:23] op_sel_hi:[1,0]
	v_pk_mul_f32 v[12:13], v[12:13], v[22:23] op_sel_hi:[1,0]
	v_mov_b32_e32 v15, v8
	v_mov_b32_e32 v8, v7
	v_mov_b32_e32 v14, v6
	v_pk_mul_f32 v[8:9], v[12:13], v[8:9]
	v_pk_mul_f32 v[6:7], v[10:11], v[14:15]
	v_and_b32_sdwa v12, v9, v53 dst_sel:DWORD dst_unused:UNUSED_PAD src0_sel:WORD_1 src1_sel:DWORD
	v_and_b32_sdwa v13, v8, v53 dst_sel:DWORD dst_unused:UNUSED_PAD src0_sel:WORD_1 src1_sel:DWORD
	v_and_b32_sdwa v10, v7, v53 dst_sel:DWORD dst_unused:UNUSED_PAD src0_sel:WORD_1 src1_sel:DWORD
	v_and_b32_sdwa v11, v6, v53 dst_sel:DWORD dst_unused:UNUSED_PAD src0_sel:WORD_1 src1_sel:DWORD
	v_add3_u32 v9, v9, v12, s20
	v_add3_u32 v8, v8, v13, s20
	v_add3_u32 v6, v6, v11, s20
	v_add3_u32 v7, v7, v10, s20
	v_and_b32_e32 v9, 0xffff0000, v9
	v_and_b32_e32 v8, 0xffff0000, v8
	v_or_b32_sdwa v7, v9, v7 dst_sel:DWORD dst_unused:UNUSED_PAD src0_sel:DWORD src1_sel:WORD_1
	v_or_b32_sdwa v6, v8, v6 dst_sel:DWORD dst_unused:UNUSED_PAD src0_sel:DWORD src1_sel:WORD_1
	global_store_dwordx2 v[40:41], v[6:7], off offset:3072
	s_nop 1
	v_mov_b64_e32 v[6:7], v[224:225]
	v_mov_b64_e32 v[8:9], v[226:227]
	v_mov_b32_e32 v10, v2
	v_mov_b32_e32 v11, v4
	v_mov_b32_e32 v4, v3
	v_pk_mul_f32 v[2:3], v[10:11], v[22:23] op_sel_hi:[1,0]
	v_pk_mul_f32 v[4:5], v[4:5], v[22:23] op_sel_hi:[1,0]
	v_mov_b32_e32 v11, v8
	v_mov_b32_e32 v8, v7
	v_mov_b32_e32 v10, v6
	v_pk_mul_f32 v[4:5], v[4:5], v[8:9]
	v_pk_mul_f32 v[2:3], v[2:3], v[10:11]
	v_and_b32_sdwa v8, v5, v53 dst_sel:DWORD dst_unused:UNUSED_PAD src0_sel:WORD_1 src1_sel:DWORD
	v_and_b32_sdwa v9, v4, v53 dst_sel:DWORD dst_unused:UNUSED_PAD src0_sel:WORD_1 src1_sel:DWORD
	v_and_b32_sdwa v6, v3, v53 dst_sel:DWORD dst_unused:UNUSED_PAD src0_sel:WORD_1 src1_sel:DWORD
	v_and_b32_sdwa v7, v2, v53 dst_sel:DWORD dst_unused:UNUSED_PAD src0_sel:WORD_1 src1_sel:DWORD
	v_add3_u32 v5, v5, v8, s20
	v_add3_u32 v4, v4, v9, s20
	v_add3_u32 v2, v2, v7, s20
	v_add3_u32 v3, v3, v6, s20
	v_and_b32_e32 v5, 0xffff0000, v5
	v_and_b32_e32 v4, 0xffff0000, v4
	v_or_b32_sdwa v3, v5, v3 dst_sel:DWORD dst_unused:UNUSED_PAD src0_sel:DWORD src1_sel:WORD_1
	v_or_b32_sdwa v2, v4, v2 dst_sel:DWORD dst_unused:UNUSED_PAD src0_sel:DWORD src1_sel:WORD_1
	global_store_dwordx2 v[40:41], v[2:3], off offset:3584
	v_lshl_add_u64 v[40:41], v[40:41], 0, s[18:19]
	s_cbranch_scc0 .LBB0_123
